# attention: two barriers per tile, waves 4-7 one barrier behind, static prio 3 on the QK+softmax segment, role-dependent K/V DMA issue with counted vmcnt
# baseline (speedup 1.0000x reference)
.LBB0_182:
	s_lshr_b32 s6, s25, 1
	s_mul_i32 s6, s24, s6
	s_add_i32 s34, s17, s6
	s_lshl_b32 s6, s34, 4
	s_and_b32 s36, s6, 0xe00
	s_and_b32 s6, s34, 31
	s_ashr_i32 s8, s34, 8
	s_and_b32 s7, s25, 1
	s_xor_b32 s9, s6, 63
	v_mov_b32_e32 v4, v0
	s_cmp_eq_u32 s7, 0
	s_cselect_b32 s80, s6, s9
	v_readfirstlane_b32 s54, v4
	s_ashr_i32 s87, s54, 6
	s_ashr_i32 s9, s8, 31
	s_ashr_i32 s56, s54, 8
	s_and_b32 s57, s87, 3
	s_lshl_b32 s58, s80, 7
	s_lshl_b64 s[6:7], s[8:9], 13
	s_mul_i32 s88, s8, 0x14000000
	s_mul_hi_i32 s37, s8, 0x14000000
	s_add_u32 s8, s38, s88
	s_addc_u32 s9, s39, s37
	s_lshl_b32 s34, s34, 3
	s_and_b32 s55, s34, 0x700
	s_lshl_b32 s60, s55, 1
	s_add_u32 s8, s8, s60
	s_addc_u32 s9, s9, 0
	s_add_u32 s34, s8, 0x1000
	s_addc_u32 s35, s9, 0
	s_add_u32 s82, s8, 0x2000
	s_addc_u32 s83, s9, 0
	s_lshl_b32 s8, s57, 5
	s_or_b32 s59, s58, s8
	s_or_b32 s6, s59, s6
	s_mul_hi_u32 s9, s6, 0xa000
	s_mul_i32 s58, s7, 0xa000
	s_mul_i32 s8, s6, 0xa000
	s_add_i32 s9, s9, s58
	s_add_u32 s8, s38, s8
	s_addc_u32 s9, s39, s9
	s_add_u32 s58, s8, s60
	s_addc_u32 s60, s9, 0
	s_lshl_b32 s8, s56, 7
	s_ashr_i32 s9, s8, 31
	v_and_b32_e32 v14, 63, v4
	s_lshl_b64 s[8:9], s[8:9], 1
	s_add_u32 s8, s58, s8
	v_mov_b32_e32 v15, v14
	s_addc_u32 s9, s60, s9
	s_lshl_b32 s68, s87, 3
	v_ashrrev_i32_e32 v6, 4, v15
	v_and_b32_e32 v7, 15, v15
	v_add_u32_e32 v2, s68, v6
	s_and_b32 s58, s54, 0x3fffffc0
	s_waitcnt lgkmcnt(0)
	v_bitop3_b32 v3, v6, v7, 7 bitop3:0x6c
	v_mul_lo_u32 v2, v2, s45
	s_lshl_b32 s58, s58, 2
	v_lshl_or_b32 v2, v3, 3, v2
	s_lshl_b32 s61, s87, 11
	s_add_i32 s60, s58, 0
	s_lshl_b32 s58, s87, 1
	s_add_i32 s62, s61, 0
	v_ashrrev_i32_e32 v3, 31, v2
	v_lshl_add_u64 v[2:3], v[2:3], 1, s[34:35]
	s_mov_b32 m0, s62
	s_add_i32 s63, s62, 0x4000
	s_or_b32 s58, s58, 1
	global_load_lds_dwordx4 v[2:3], off
	v_lshl_add_u64 v[2:3], v[2:3], 0, s[12:13]
	s_mov_b32 m0, s63
	s_lshl_b32 s64, s58, 2
	global_load_lds_dwordx4 v[2:3], off
	v_add_u32_e32 v2, s64, v6
	v_bitop3_b32 v3, v2, v7, 7 bitop3:0x6c
	v_mul_lo_u32 v2, v2, s45
	v_lshl_or_b32 v2, v3, 3, v2
	s_lshl_b32 s65, s58, 10
	s_add_i32 s66, s65, 0
	v_ashrrev_i32_e32 v3, 31, v2
	s_andn2_b32 s68, s68, 31
	s_add_i32 s60, s60, 0x20400
	v_lshl_add_u64 v[2:3], v[2:3], 1, s[34:35]
	s_add_i32 s67, s66, 0x4000
	s_lshl_b32 s58, s87, 2
	s_mul_i32 s35, s68, 0xa000
	s_mul_hi_i32 s34, s68, 0xa000
	s_add_u32 s35, s82, s35
	s_mov_b32 m0, s66
	s_addc_u32 s69, s83, s34
	s_and_b32 s34, s54, 0x80
	global_load_lds_dwordx4 v[2:3], off
	v_lshl_add_u64 v[2:3], v[2:3], 0, s[12:13]
	s_mov_b32 m0, s67
	s_lshl_b32 s84, s34, 1
	global_load_lds_dwordx4 v[2:3], off
	v_lshrrev_b32_e32 v2, 2, v15
	s_add_u32 s34, s35, s84
	s_addc_u32 s35, s69, 0
	s_lshl_b32 s69, s87, 4
	v_bfe_u32 v2, v2, 2, 1
	v_bfe_u32 v16, v15, 2, 3
	s_and_b32 s69, s69, 16
	v_xor_b32_e32 v2, v2, v15
	v_or_b32_e32 v6, s69, v16
	v_and_b32_e32 v17, 0xffffffe0, v15
	v_lshlrev_b32_e32 v2, 3, v2
	v_and_b32_e32 v12, 24, v2
	v_mad_u32_u24 v2, v6, s45, v17
	s_lshl_b32 s70, s87, 12
	v_or_b32_e32 v2, v12, v2
	s_add_i32 s72, s70, 0
	v_ashrrev_i32_e32 v3, 31, v2
	s_add_i32 s71, s72, 0x8000
	v_and_b32_e32 v5, 31, v4
	v_lshl_add_u64 v[2:3], v[2:3], 1, s[34:35]
	s_mov_b32 m0, s71
	v_add_u32_e32 v18, 64, v17
	global_load_lds_dwordx4 v[2:3], off
	v_mul_u32_u24_e32 v2, 0x5000, v5
	v_mad_u32_u24 v13, v6, s45, v18
	v_lshlrev_b32_e32 v222, 1, v2
	v_lshl_add_u64 v[2:3], s[8:9], 0, v[222:223]
	v_lshrrev_b32_e32 v4, 1, v4
	v_or_b32_e32 v12, v12, v13
	s_or_b32 s8, s58, 2
	v_and_b32_e32 v222, 16, v4
	v_ashrrev_i32_e32 v13, 31, v12
	s_add_i32 s72, s72, 0x8400
	s_lshl_b32 s9, s8, 2
	v_lshl_add_u64 v[10:11], v[2:3], 0, v[222:223]
	v_lshl_add_u64 v[12:13], v[12:13], 1, s[34:35]
	s_mov_b32 m0, s72
	s_and_b32 s73, s9, 24
	global_load_dwordx4 v[2:5], v[10:11], off offset:192
	global_load_dwordx4 v[6:9], v[10:11], off offset:224
	s_lshl_b32 s74, s8, 10
	global_load_lds_dwordx4 v[12:13], off
	v_or_b32_e32 v12, s73, v16
	v_lshrrev_b32_e32 v13, 2, v12
	v_xor_b32_e32 v13, v13, v15
	v_lshlrev_b32_e32 v13, 3, v13
	v_mad_u32_u24 v12, v12, s45, v17
	v_and_or_b32 v12, v13, 24, v12
	s_add_i32 s75, s74, 0
	s_or_b32 s8, s58, 3
	v_ashrrev_i32_e32 v13, 31, v12
	s_add_i32 s75, s75, 0x8000
	s_lshl_b32 s9, s8, 2
	v_lshl_add_u64 v[12:13], v[12:13], 1, s[34:35]
	s_mov_b32 m0, s75
	s_and_b32 s76, s9, 24
	global_load_lds_dwordx4 v[12:13], off
	v_or_b32_e32 v12, s76, v16
	v_lshrrev_b32_e32 v13, 2, v12
	v_xor_b32_e32 v13, v13, v15
	v_lshlrev_b32_e32 v13, 3, v13
	v_mad_u32_u24 v12, v12, s45, v18
	s_lshl_b32 s77, s8, 10
	v_and_or_b32 v12, v13, 24, v12
	s_add_i32 s78, s77, 0
	v_ashrrev_i32_e32 v13, 31, v12
	s_add_i32 s78, s78, 0x8000
	v_lshl_add_u64 v[12:13], v[12:13], 1, s[34:35]
	s_mov_b32 m0, s78
	s_lshl_b32 s80, s80, 1
	global_load_lds_dwordx4 v[12:13], off
	global_load_dwordx4 v[34:37], v[10:11], off
	global_load_dwordx4 v[38:41], v[10:11], off offset:32
	global_load_dwordx4 v[42:45], v[10:11], off offset:64
	global_load_dwordx4 v[46:49], v[10:11], off offset:96
	global_load_dwordx4 v[50:53], v[10:11], off offset:128
	global_load_dwordx4 v[54:57], v[10:11], off offset:160
	s_add_i32 s81, s62, 0x22400
	s_add_u32 s82, s82, s84
	s_addc_u32 s83, s83, 0
	s_lshl_b32 s8, s56, 14
	s_add_i32 s84, s8, 0
	s_add_i32 s85, s84, 0x10000
	s_add_i32 s86, s59, 0x7fffffff
	s_or_b32 s8, s88, s36
	s_mul_i32 s87, s87, 0x28000
	s_add_u32 s8, s43, s8
	s_mov_b32 s79, 0
	v_lshl_add_u32 v10, v14, 4, s81
	s_addc_u32 s9, s44, s37
	s_add_i32 s88, s87, 0x14000
	v_mov_b32_e32 v186, 0xf149f2ca
	s_mov_b32 s89, 0
	v_mov_b32_e32 v187, 0
	s_waitcnt vmcnt(0)
	ds_write_b128 v10, v[2:5]
	ds_write_b128 v10, v[6:9] offset:1024
	v_mov_b32 v58, 0
	v_mov_b32 v59, 0
	v_mov_b32 v60, 0
	v_mov_b32 v61, 0
	v_mov_b32 v62, 0
	v_mov_b32 v63, 0
	v_mov_b32 v64, 0
	v_mov_b32 v65, 0
	v_mov_b32 v66, 0
	v_mov_b32 v67, 0
	v_mov_b32 v68, 0
	v_mov_b32 v69, 0
	v_mov_b32 v70, 0
	v_mov_b32 v71, 0
	v_mov_b32 v72, 0
	v_mov_b32 v73, 0
	v_mov_b32 v74, 0
	v_mov_b32 v75, 0
	v_mov_b32 v76, 0
	v_mov_b32 v77, 0
	v_mov_b32 v82, 0
	v_mov_b32 v83, 0
	v_mov_b32 v84, 0
	v_mov_b32 v85, 0
	v_mov_b32 v90, 0
	v_mov_b32 v91, 0
	v_mov_b32 v92, 0
	v_mov_b32 v93, 0
	v_mov_b32 v98, 0
	v_mov_b32 v99, 0
	v_mov_b32 v100, 0
	v_mov_b32 v101, 0
	v_mov_b32 v110, 0
	v_mov_b32 v111, 0
	v_mov_b32 v112, 0
	v_mov_b32 v113, 0
	v_mov_b32 v122, 0
	v_mov_b32 v123, 0
	v_mov_b32 v124, 0
	v_mov_b32 v125, 0
	v_mov_b32 v134, 0
	v_mov_b32 v135, 0
	v_mov_b32 v136, 0
	v_mov_b32 v137, 0
	v_mov_b32 v146, 0
	v_mov_b32 v147, 0
	v_mov_b32 v148, 0
	v_mov_b32 v149, 0
	v_mov_b32 v158, 0
	v_mov_b32 v159, 0
	v_mov_b32 v160, 0
	v_mov_b32 v161, 0
	v_mov_b32 v174, 0
	v_mov_b32 v175, 0
	v_mov_b32 v176, 0
	v_mov_b32 v177, 0
	v_mov_b32 v182, 0
	v_mov_b32 v183, 0
	v_mov_b32 v184, 0
	v_mov_b32 v185, 0
	v_mov_b32 v170, 0
	v_mov_b32 v171, 0
	v_mov_b32 v172, 0
	v_mov_b32 v173, 0
	v_mov_b32 v178, 0
	v_mov_b32 v179, 0
	v_mov_b32 v180, 0
	v_mov_b32 v181, 0
	v_mov_b32 v166, 0
	v_mov_b32 v167, 0
	v_mov_b32 v168, 0
	v_mov_b32 v169, 0
	v_mov_b32 v162, 0
	v_mov_b32 v163, 0
	v_mov_b32 v164, 0
	v_mov_b32 v165, 0
	v_mov_b32 v154, 0
	v_mov_b32 v155, 0
	v_mov_b32 v156, 0
	v_mov_b32 v157, 0
	v_mov_b32 v150, 0
	v_mov_b32 v151, 0
	v_mov_b32 v152, 0
	v_mov_b32 v153, 0
	v_mov_b32 v142, 0
	v_mov_b32 v143, 0
	v_mov_b32 v144, 0
	v_mov_b32 v145, 0
	v_mov_b32 v138, 0
	v_mov_b32 v139, 0
	v_mov_b32 v140, 0
	v_mov_b32 v141, 0
	v_mov_b32 v130, 0
	v_mov_b32 v131, 0
	v_mov_b32 v132, 0
	v_mov_b32 v133, 0
	v_mov_b32 v126, 0
	v_mov_b32 v127, 0
	v_mov_b32 v128, 0
	v_mov_b32 v129, 0
	v_mov_b32 v118, 0
	v_mov_b32 v119, 0
	v_mov_b32 v120, 0
	v_mov_b32 v121, 0
	v_mov_b32 v114, 0
	v_mov_b32 v115, 0
	v_mov_b32 v116, 0
	v_mov_b32 v117, 0
	v_mov_b32 v106, 0
	v_mov_b32 v107, 0
	v_mov_b32 v108, 0
	v_mov_b32 v109, 0
	v_mov_b32 v102, 0
	v_mov_b32 v103, 0
	v_mov_b32 v104, 0
	v_mov_b32 v105, 0
	v_mov_b32 v94, 0
	v_mov_b32 v95, 0
	v_mov_b32 v96, 0
	v_mov_b32 v97, 0
	v_mov_b32 v86, 0
	v_mov_b32 v87, 0
	v_mov_b32 v88, 0
	v_mov_b32 v89, 0
	v_mov_b32 v78, 0
	v_mov_b32 v79, 0
	v_mov_b32 v80, 0
	v_mov_b32 v81, 0
	s_cmp_lt_u32 s19, 4
	s_cbranch_scc1 .Lstag_pre_skip
	s_waitcnt vmcnt(0)
	s_barrier
	s_add_u32 s98, s8, s14
	s_addc_u32 s99, s9, s15
	s_add_u32 s100, s8, s28
	s_addc_u32 s101, s9, s29
	s_add_i32 s36, s61, 0x10000
	s_mov_b32 m0, s36
	s_add_i32 s37, s36, 0x4000
	global_load_lds_dwordx4 v251, s[98:99]
	s_mov_b32 m0, s37
	s_add_i32 s36, s65, 0x10000
	global_load_lds_dwordx4 v251, s[100:101]
	s_mov_b32 m0, s36
	s_add_i32 s37, s36, 0x4000
	global_load_lds_dwordx4 v252, s[98:99]
	s_mov_b32 m0, s37
	s_nop 0
	global_load_lds_dwordx4 v252, s[100:101]
.Lstag_pre_skip:
	s_branch .LBB0_185

.LBB0_184:
	s_cmp_ge_u32 s89, s80
	s_cbranch_scc1 .Ls1b2_nomore
	s_setprio 0
	s_waitcnt vmcnt(4)
	s_barrier
	s_cmp_lt_u32 s19, 4
	s_cbranch_scc0 .Ls1b2_lag
	s_add_i32 s36, s68, s79
	s_addk_i32 s36, 0x80
	s_mul_hi_i32 s37, s36, 0xa000
	s_mul_i32 s36, s36, 0xa000
	s_add_u32 s36, s82, s36
	s_addc_u32 s37, s83, s37
	s_add_u32 s98, s36, 0x80
	s_addc_u32 s99, s37, 0
	s_mov_b32 m0, s71
	s_nop 0
	global_load_lds_dwordx4 v253, s[36:37]
	s_mov_b32 m0, s72
	s_nop 0
	global_load_lds_dwordx4 v253, s[98:99]
	s_mov_b32 m0, s75
	s_nop 0
	global_load_lds_dwordx4 v254, s[36:37]
	s_mov_b32 m0, s78
	s_nop 0
	global_load_lds_dwordx4 v254, s[98:99]
	s_branch .Ls1b2_done
.Ls1b2_lag:
	s_add_u32 s98, s8, 0x500000
	s_addc_u32 s99, s9, 0
	s_add_u32 s100, s98, s28
	s_addc_u32 s101, s99, s29
	s_add_u32 s98, s98, s14
	s_addc_u32 s99, s99, s15
	s_add_i32 s36, s61, 0x10000
	s_mov_b32 m0, s36
	s_add_i32 s37, s36, 0x4000
	global_load_lds_dwordx4 v251, s[98:99]
	s_mov_b32 m0, s37
	s_add_i32 s36, s65, 0x10000
	global_load_lds_dwordx4 v251, s[100:101]
	s_mov_b32 m0, s36
	s_add_i32 s37, s36, 0x4000
	global_load_lds_dwordx4 v252, s[98:99]
	s_mov_b32 m0, s37
	s_nop 0
	global_load_lds_dwordx4 v252, s[100:101]
	s_branch .Ls1b2_done
.Ls1b2_nomore:
	s_setprio 0
	s_waitcnt vmcnt(0)
	s_barrier

.LBB0_185:
	s_waitcnt vmcnt(4)
	s_barrier
	s_setprio 3
	v_mbcnt_lo_u32_b32 v192, -1, 0
	v_mbcnt_hi_u32_b32 v192, -1, v192
	s_cmp_lt_u32 s19, 4
	s_cbranch_scc0 .Ls0b1_lag
	s_add_u32 s98, s8, s14
	s_addc_u32 s99, s9, s15
	s_add_u32 s100, s8, s28
	s_addc_u32 s101, s9, s29
	s_add_i32 s36, s61, 0x10000
	s_mov_b32 m0, s36
	s_add_i32 s37, s36, 0x4000
	global_load_lds_dwordx4 v251, s[98:99]
	s_mov_b32 m0, s37
	s_add_i32 s36, s65, 0x10000
	global_load_lds_dwordx4 v251, s[100:101]
	s_mov_b32 m0, s36
	s_add_i32 s37, s36, 0x4000
	global_load_lds_dwordx4 v252, s[98:99]
	s_mov_b32 m0, s37
	s_nop 0
	global_load_lds_dwordx4 v252, s[100:101]
	s_branch .Ls0b1_done
.Ls0b1_lag:
	s_add_i32 s36, s68, s79
	s_add_i32 s90, s36, 64
	s_mul_hi_i32 s91, s90, 0xa000
	s_mul_i32 s90, s90, 0xa000
	s_add_u32 s90, s82, s90
	s_addc_u32 s91, s83, s91
	s_add_u32 s98, s90, 0x80
	s_addc_u32 s99, s91, 0
	s_add_i32 s94, s47, s70
	s_mov_b32 m0, s94
	s_add_i32 s95, s94, 0x400
	global_load_lds_dwordx4 v253, s[90:91]
	s_mov_b32 m0, s95
	s_add_i32 s96, s47, s74
	global_load_lds_dwordx4 v253, s[98:99]
	s_mov_b32 m0, s96
	s_add_i32 s97, s47, s77
	global_load_lds_dwordx4 v254, s[90:91]
	s_mov_b32 m0, s97
	s_nop 0
	global_load_lds_dwordx4 v254, s[98:99]
.Ls0b1_done:
	s_add_i32 s34, s79, 63
	v_ashrrev_i32_e32 v188, 5, v192
	v_and_b32_e32 v193, 31, v192
	v_lshlrev_b32_e32 v189, 4, v192
	v_lshlrev_b32_e32 v191, 4, v188
	v_lshlrev_b32_e32 v190, 8, v193
	v_bitop3_b32 v2, v189, v191, s48 bitop3:0x6c
	v_add3_u32 v6, s84, v2, v190
	ds_read_b128 v[2:5], v6
	ds_read_b128 v[194:197], v6 offset:128
	s_waitcnt lgkmcnt(0)
	v_mfma_f32_32x32x16_bf16 v[18:33], v[2:5], v[34:37], 0
	ds_read_b128 v[2:5], v6 offset:8192
	ds_read_b128 v[198:201], v6 offset:8320
	v_add_u32_e32 v7, 32, v191
	v_bitop3_b32 v7, v7, v189, s48 bitop3:0x78
	v_add3_u32 v210, s84, v7, v190
	ds_read_b128 v[202:205], v210
	ds_read_b128 v[206:209], v210 offset:128
	v_add_u32_e32 v211, 64, v191
	s_waitcnt lgkmcnt(0)
	v_mfma_f32_32x32x16_bf16 v[18:33], v[202:205], v[38:41], v[18:33]
	ds_read_b128 v[202:205], v210 offset:8192
	v_bitop3_b32 v211, v211, v189, s48 bitop3:0x78
	v_add3_u32 v218, s84, v211, v190
	ds_read_b128 v[210:213], v210 offset:8320
	v_add_u32_e32 v191, 0x60, v191
	v_bitop3_b32 v191, v191, v189, s48 bitop3:0x78
	v_add3_u32 v190, s84, v191, v190
	v_mfma_f32_32x32x16_bf16 v[2:17], v[2:5], v[34:37], 0
	v_add_u32_e32 v189, s81, v189
	s_cmp_le_u32 s34, s59
	s_waitcnt lgkmcnt(0)
	v_mfma_f32_32x32x16_bf16 v[2:17], v[202:205], v[38:41], v[2:17]
	ds_read_b128 v[202:205], v218
	ds_read_b128 v[214:217], v218 offset:128
	s_waitcnt lgkmcnt(0)
	v_mfma_f32_32x32x16_bf16 v[18:33], v[202:205], v[42:45], v[18:33]
	ds_read_b128 v[202:205], v218 offset:8192
	ds_read_b128 v[218:221], v218 offset:8320
	s_waitcnt lgkmcnt(0)
	v_mfma_f32_32x32x16_bf16 v[2:17], v[202:205], v[42:45], v[2:17]
	ds_read_b128 v[202:205], v190
	ds_read_b128 v[226:229], v190 offset:128
	s_waitcnt lgkmcnt(0)
	v_mfma_f32_32x32x16_bf16 v[18:33], v[202:205], v[46:49], v[18:33]
	ds_read_b128 v[202:205], v190 offset:8192
	ds_read_b128 v[230:233], v190 offset:8320
	s_waitcnt lgkmcnt(0)
	v_mfma_f32_32x32x16_bf16 v[2:17], v[202:205], v[46:49], v[2:17]
	v_mfma_f32_32x32x16_bf16 v[18:33], v[194:197], v[50:53], v[18:33]
	v_mfma_f32_32x32x16_bf16 v[2:17], v[198:201], v[50:53], v[2:17]
	ds_read_b128 v[194:197], v189
	ds_read_b128 v[198:201], v189 offset:1024
	v_mfma_f32_32x32x16_bf16 v[18:33], v[206:209], v[54:57], v[18:33]
	v_mfma_f32_32x32x16_bf16 v[2:17], v[210:213], v[54:57], v[2:17]
	s_waitcnt lgkmcnt(0)
	v_mfma_f32_32x32x16_bf16 v[18:33], v[214:217], v[194:197], v[18:33]
	v_mfma_f32_32x32x16_bf16 v[2:17], v[218:221], v[194:197], v[2:17]
	v_mfma_f32_32x32x16_bf16 v[18:33], v[226:229], v[198:201], v[18:33]
	v_mfma_f32_32x32x16_bf16 v[2:17], v[230:233], v[198:201], v[2:17]
	s_cbranch_scc1 .LBB0_187
	v_lshlrev_b32_e32 v188, 2, v188
	v_sub_u32_e32 v188, v193, v188
	v_add_u32_e32 v188, s86, v188
	v_add_u32_e32 v189, 0x80000001, v188
	v_cmp_gt_u32_e32 vcc, s46, v189
	s_nop 4
	v_cndmask_b32_e32 v18, v225, v18, vcc
	v_cmp_lt_i32_e32 vcc, 31, v189
	s_nop 1
	v_cndmask_b32_e32 v2, v225, v2, vcc
	v_cmp_lt_i32_e32 vcc, 0, v189
	v_subrev_u32_e32 v189, 31, v188
	s_nop 0
	v_cndmask_b32_e32 v19, v225, v19, vcc
	v_cmp_lt_u32_e32 vcc, s49, v189
	v_subrev_u32_e32 v189, 32, v188
	s_nop 0
	v_cndmask_b32_e32 v3, v225, v3, vcc
	v_cmp_lt_u32_e32 vcc, s49, v188
	s_nop 1
	v_cndmask_b32_e32 v20, v225, v20, vcc
	v_cmp_lt_u32_e32 vcc, s49, v189
	v_add_u32_e32 v189, -1, v188
	s_nop 0
	v_cndmask_b32_e32 v4, v225, v4, vcc
	v_cmp_lt_u32_e32 vcc, s49, v189
	v_subrev_u32_e32 v189, 33, v188
	s_nop 0
	v_cndmask_b32_e32 v21, v225, v21, vcc
	v_cmp_lt_u32_e32 vcc, s49, v189
	v_add_u32_e32 v189, -6, v188
	s_nop 0
	v_cndmask_b32_e32 v5, v225, v5, vcc
	v_cmp_lt_u32_e32 vcc, s49, v189
	v_subrev_u32_e32 v189, 38, v188
	s_nop 0
	v_cndmask_b32_e32 v22, v225, v22, vcc
	v_cmp_lt_u32_e32 vcc, s49, v189
	v_add_u32_e32 v189, -7, v188
	s_nop 0
	v_cndmask_b32_e32 v6, v225, v6, vcc
	v_cmp_lt_u32_e32 vcc, s49, v189
	v_subrev_u32_e32 v189, 39, v188
	s_nop 0
	v_cndmask_b32_e32 v23, v225, v23, vcc
	v_cmp_lt_u32_e32 vcc, s49, v189
	v_add_u32_e32 v189, -8, v188
	s_nop 0
	v_cndmask_b32_e32 v7, v225, v7, vcc
	v_cmp_lt_u32_e32 vcc, s49, v189
	v_subrev_u32_e32 v189, 40, v188
	s_nop 0
	v_cndmask_b32_e32 v24, v225, v24, vcc
	v_cmp_lt_u32_e32 vcc, s49, v189
	v_add_u32_e32 v189, -9, v188
	s_nop 0
	v_cndmask_b32_e32 v8, v225, v8, vcc
	v_cmp_lt_u32_e32 vcc, s49, v189
	v_subrev_u32_e32 v189, 41, v188
	s_nop 0
	v_cndmask_b32_e32 v25, v225, v25, vcc
	v_cmp_lt_u32_e32 vcc, s49, v189
	v_add_u32_e32 v189, -14, v188
	s_nop 0
	v_cndmask_b32_e32 v9, v225, v9, vcc
	v_cmp_lt_u32_e32 vcc, s49, v189
	v_subrev_u32_e32 v189, 46, v188
	s_nop 0
	v_cndmask_b32_e32 v26, v225, v26, vcc
	v_cmp_lt_u32_e32 vcc, s49, v189
	v_add_u32_e32 v189, -15, v188
	s_nop 0
	v_cndmask_b32_e32 v10, v225, v10, vcc
	v_cmp_lt_u32_e32 vcc, s49, v189
	v_subrev_u32_e32 v189, 47, v188
	s_nop 0
	v_cndmask_b32_e32 v27, v225, v27, vcc
	v_cmp_lt_u32_e32 vcc, s49, v189
	v_add_u32_e32 v189, -16, v188
	s_nop 0
	v_cndmask_b32_e32 v11, v225, v11, vcc
	v_cmp_lt_u32_e32 vcc, s49, v189
	v_subrev_u32_e32 v189, 48, v188
	s_nop 0
	v_cndmask_b32_e32 v28, v225, v28, vcc
	v_cmp_lt_u32_e32 vcc, s49, v189
	v_subrev_u32_e32 v189, 17, v188
	s_nop 0
	v_cndmask_b32_e32 v12, v225, v12, vcc
	v_cmp_lt_u32_e32 vcc, s49, v189
	v_subrev_u32_e32 v189, 49, v188
	s_nop 0
	v_cndmask_b32_e32 v29, v225, v29, vcc
	v_cmp_lt_u32_e32 vcc, s49, v189
	v_subrev_u32_e32 v189, 22, v188
	s_nop 0
	v_cndmask_b32_e32 v13, v225, v13, vcc
	v_cmp_lt_u32_e32 vcc, s49, v189
	v_subrev_u32_e32 v189, 54, v188
	s_nop 0
	v_cndmask_b32_e32 v30, v225, v30, vcc
	v_cmp_lt_u32_e32 vcc, s49, v189
	v_subrev_u32_e32 v189, 23, v188
	s_nop 0
	v_cndmask_b32_e32 v14, v225, v14, vcc
	v_cmp_lt_u32_e32 vcc, s49, v189
	v_subrev_u32_e32 v189, 55, v188
	s_nop 0
	v_cndmask_b32_e32 v31, v225, v31, vcc
	v_cmp_lt_u32_e32 vcc, s49, v189
	v_subrev_u32_e32 v189, 24, v188
	s_nop 0
	v_cndmask_b32_e32 v15, v225, v15, vcc
	v_cmp_lt_u32_e32 vcc, s49, v189
	v_subrev_u32_e32 v189, 56, v188
	s_nop 0
	v_cndmask_b32_e32 v32, v225, v32, vcc
	v_cmp_lt_u32_e32 vcc, s49, v189
	v_subrev_u32_e32 v189, 25, v188
	v_subrev_u32_e32 v188, 57, v188
	v_cndmask_b32_e32 v16, v225, v16, vcc
	v_cmp_lt_u32_e32 vcc, s49, v189
	s_nop 1
	v_cndmask_b32_e32 v33, v225, v33, vcc
	v_cmp_lt_u32_e32 vcc, s49, v188
	s_nop 1
	v_cndmask_b32_e32 v17, v225, v17, vcc

.LBB0_192:
	s_setprio 0
	s_waitcnt vmcnt(4)
	s_barrier
	s_cmp_lt_u32 s19, 4
	s_cbranch_scc0 .Ls0b2_lag
	s_add_i32 s36, s68, s79
	s_add_i32 s90, s36, 64
	s_mul_hi_i32 s91, s90, 0xa000
	s_mul_i32 s90, s90, 0xa000
	s_add_u32 s90, s82, s90
	s_addc_u32 s91, s83, s91
	s_add_u32 s98, s90, 0x80
	s_addc_u32 s99, s91, 0
	s_add_i32 s94, s47, s70
	s_mov_b32 m0, s94
	s_add_i32 s95, s94, 0x400
	global_load_lds_dwordx4 v253, s[90:91]
	s_mov_b32 m0, s95
	s_add_i32 s96, s47, s74
	global_load_lds_dwordx4 v253, s[98:99]
	s_mov_b32 m0, s96
	s_add_i32 s97, s47, s77
	global_load_lds_dwordx4 v254, s[90:91]
	s_mov_b32 m0, s97
	s_nop 0
	global_load_lds_dwordx4 v254, s[98:99]
	s_branch .Ls0b2_done
.Ls0b2_lag:
	s_cmp_ge_u32 s89, s80
	s_cbranch_scc1 .Ls0b2_done
	s_add_u32 s98, s8, s30
	s_addc_u32 s99, s9, s31
	s_mov_b32 m0, s62
	s_nop 0
	global_load_lds_dwordx4 v251, s[98:99]
	s_mov_b32 m0, s63
	s_nop 0
	global_load_lds_dwordx4 v251, s[8:9]
	s_mov_b32 m0, s66
	s_nop 0
	global_load_lds_dwordx4 v252, s[98:99]
	s_mov_b32 m0, s67
	s_nop 0
	global_load_lds_dwordx4 v252, s[8:9]
.Ls0b2_done:
	s_cmp_lg_u32 0, -1
	v_lshrrev_b32_e32 v18, 3, v192
	v_ashrrev_i32_e32 v19, 5, v192
	v_and_or_b32 v18, v18, 2, v19
	v_lshlrev_b32_e32 v19, 1, v19
	v_lshrrev_b32_e32 v20, 1, v192
	v_bfe_u32 v21, v192, 1, 1
	v_and_b32_e32 v19, 2, v19
	v_and_b32_e32 v22, 12, v192
	v_or3_b32 v21, v22, v19, v21
	v_bitop3_b32 v19, v19, v20, 1 bitop3:0x72
	v_lshlrev_b32_e32 v18, 11, v18
	v_lshlrev_b32_e32 v23, 3, v192
	v_or_b32_e32 v19, v19, v22
	s_cselect_b32 s34, 0, 0
	v_and_b32_e32 v23, 8, v23
	v_lshl_or_b32 v19, v19, 4, v18
	s_add_i32 s34, s34, 0x8000
	v_lshlrev_b32_e32 v21, 4, v21
	v_or3_b32 v19, v19, v23, s51
	v_add_u32_e32 v20, s34, v23
	s_waitcnt lgkmcnt(0)
	v_add3_u32 v220, v20, v18, v21
	v_add_u32_e32 v221, s34, v19
	ds_read_b64_tr_b16 v[18:19], v220 offset:0
	ds_read_b64_tr_b16 v[20:21], v221 offset:0
	v_xor_b32_e32 v222, 32, v220
	ds_read_b64_tr_b16 v[22:23], v222 offset:0
	v_xor_b32_e32 v250, 32, v221
	ds_read_b64_tr_b16 v[24:25], v250 offset:0
	ds_read_b64_tr_b16 v[26:27], v220 offset:0x200
	ds_read_b64_tr_b16 v[28:29], v221 offset:0x200
	s_waitcnt lgkmcnt(4)
	v_permlane16_swap_b32_e32 v10, v14
	v_permlane16_swap_b32_e32 v11, v15
	v_permlane16_swap_b32_e32 v12, v16
	v_permlane16_swap_b32_e32 v13, v17
	v_permlane16_swap_b32_e32 v2, v6
	v_permlane16_swap_b32_e32 v3, v7
	v_permlane16_swap_b32_e32 v4, v8
	v_permlane16_swap_b32_e32 v5, v9
	v_mfma_f32_16x16x32_bf16 v[30:33], v[10:13], v[18:21], v[58:61]
	v_mfma_f32_16x16x32_bf16 v[18:21], v[14:17], v[18:21], v[178:181]
	ds_read_b64_tr_b16 v[58:59], v222 offset:0x200
	ds_read_b64_tr_b16 v[60:61], v250 offset:0x200
	s_waitcnt lgkmcnt(4)
	v_mfma_f32_16x16x32_bf16 v[62:65], v[10:13], v[22:25], v[62:65]
	v_mfma_f32_16x16x32_bf16 v[22:25], v[14:17], v[22:25], v[166:169]
	ds_read_b64_tr_b16 v[166:167], v220 offset:0x400
	ds_read_b64_tr_b16 v[168:169], v221 offset:0x400
	s_waitcnt lgkmcnt(4)
	v_mfma_f32_16x16x32_bf16 v[66:69], v[10:13], v[26:29], v[66:69]
	v_mfma_f32_16x16x32_bf16 v[26:29], v[14:17], v[26:29], v[162:165]
	ds_read_b64_tr_b16 v[162:163], v222 offset:0x400
	ds_read_b64_tr_b16 v[164:165], v250 offset:0x400
	s_waitcnt lgkmcnt(4)
	v_mfma_f32_16x16x32_bf16 v[70:73], v[10:13], v[58:61], v[70:73]
	v_mfma_f32_16x16x32_bf16 v[58:61], v[14:17], v[58:61], v[154:157]
	ds_read_b64_tr_b16 v[154:155], v220 offset:0x600
	ds_read_b64_tr_b16 v[156:157], v221 offset:0x600
	s_waitcnt lgkmcnt(4)
	v_mfma_f32_16x16x32_bf16 v[178:181], v[10:13], v[166:169], v[74:77]
	v_mfma_f32_16x16x32_bf16 v[150:153], v[14:17], v[166:169], v[150:153]
	ds_read_b64_tr_b16 v[74:75], v222 offset:0x600
	ds_read_b64_tr_b16 v[76:77], v250 offset:0x600
	s_waitcnt lgkmcnt(4)
	v_mfma_f32_16x16x32_bf16 v[166:169], v[10:13], v[162:165], v[82:85]
	v_mfma_f32_16x16x32_bf16 v[162:165], v[14:17], v[162:165], v[142:145]
	ds_read_b64_tr_b16 v[82:83], v220 offset:0x2000
	ds_read_b64_tr_b16 v[84:85], v221 offset:0x2000
	s_waitcnt lgkmcnt(4)
	v_mfma_f32_16x16x32_bf16 v[192:195], v[10:13], v[154:157], v[90:93]
	v_mfma_f32_16x16x32_bf16 v[154:157], v[14:17], v[154:157], v[138:141]
	ds_read_b64_tr_b16 v[90:91], v222 offset:0x2000
	ds_read_b64_tr_b16 v[92:93], v250 offset:0x2000
	s_waitcnt lgkmcnt(4)
	v_mfma_f32_16x16x32_bf16 v[196:199], v[10:13], v[74:77], v[98:101]
	v_mfma_f32_16x16x32_bf16 v[200:203], v[14:17], v[74:77], v[130:133]
	ds_read_b64_tr_b16 v[74:75], v220 offset:0x2200
	ds_read_b64_tr_b16 v[76:77], v221 offset:0x2200
	s_waitcnt lgkmcnt(4)
	v_mfma_f32_16x16x32_bf16 v[110:113], v[10:13], v[82:85], v[110:113]
	v_mfma_f32_16x16x32_bf16 v[126:129], v[14:17], v[82:85], v[126:129]
	ds_read_b64_tr_b16 v[82:83], v222 offset:0x2200
	ds_read_b64_tr_b16 v[84:85], v250 offset:0x2200
	s_waitcnt lgkmcnt(4)
	v_mfma_f32_16x16x32_bf16 v[122:125], v[10:13], v[90:93], v[122:125]
	v_mfma_f32_16x16x32_bf16 v[118:121], v[14:17], v[90:93], v[118:121]
	ds_read_b64_tr_b16 v[90:91], v220 offset:0x2400
	ds_read_b64_tr_b16 v[92:93], v221 offset:0x2400
	s_waitcnt lgkmcnt(4)
	v_mfma_f32_16x16x32_bf16 v[204:207], v[10:13], v[74:77], v[134:137]
	v_mfma_f32_16x16x32_bf16 v[208:211], v[14:17], v[74:77], v[114:117]
	ds_read_b64_tr_b16 v[74:75], v222 offset:0x2400
	ds_read_b64_tr_b16 v[76:77], v250 offset:0x2400
	s_waitcnt lgkmcnt(4)
	v_mfma_f32_16x16x32_bf16 v[212:215], v[10:13], v[82:85], v[146:149]
	v_mfma_f32_16x16x32_bf16 v[216:219], v[14:17], v[82:85], v[106:109]
	ds_read_b64_tr_b16 v[82:83], v220 offset:0x2600
	ds_read_b64_tr_b16 v[84:85], v221 offset:0x2600
	s_waitcnt lgkmcnt(4)
	v_mfma_f32_16x16x32_bf16 v[226:229], v[10:13], v[90:93], v[158:161]
	v_mfma_f32_16x16x32_bf16 v[230:233], v[14:17], v[90:93], v[102:105]
	ds_read_b64_tr_b16 v[90:91], v222 offset:0x2600
	ds_read_b64_tr_b16 v[92:93], v250 offset:0x2600
	s_waitcnt lgkmcnt(4)
	v_mfma_f32_16x16x32_bf16 v[234:237], v[10:13], v[74:77], v[174:177]
	v_mfma_f32_16x16x32_bf16 v[238:241], v[14:17], v[74:77], v[94:97]
	ds_read_b64_tr_b16 v[94:95], v220 offset:0x4000
	ds_read_b64_tr_b16 v[96:97], v221 offset:0x4000
	s_waitcnt lgkmcnt(4)
	v_mfma_f32_16x16x32_bf16 v[242:245], v[10:13], v[82:85], v[182:185]
	v_mfma_f32_16x16x32_bf16 v[246:249], v[14:17], v[82:85], v[86:89]
	ds_read_b64_tr_b16 v[82:83], v222 offset:0x4000
	ds_read_b64_tr_b16 v[84:85], v250 offset:0x4000
	s_waitcnt lgkmcnt(4)
	v_mfma_f32_16x16x32_bf16 v[10:13], v[10:13], v[90:93], v[170:173]
	v_mfma_f32_16x16x32_bf16 v[14:17], v[14:17], v[90:93], v[78:81]
	ds_read_b64_tr_b16 v[86:87], v220 offset:0x4200
	ds_read_b64_tr_b16 v[88:89], v221 offset:0x4200
	s_waitcnt lgkmcnt(4)
	v_mfma_f32_16x16x32_bf16 v[74:77], v[2:5], v[94:97], v[30:33]
	v_mfma_f32_16x16x32_bf16 v[130:133], v[6:9], v[94:97], v[18:21]
	ds_read_b64_tr_b16 v[18:19], v222 offset:0x4200
	ds_read_b64_tr_b16 v[20:21], v250 offset:0x4200
	s_waitcnt lgkmcnt(4)
	v_mfma_f32_16x16x32_bf16 v[78:81], v[2:5], v[82:85], v[62:65]
	v_mfma_f32_16x16x32_bf16 v[134:137], v[6:9], v[82:85], v[22:25]
	ds_read_b64_tr_b16 v[22:23], v220 offset:0x4400
	ds_read_b64_tr_b16 v[24:25], v221 offset:0x4400
	s_waitcnt lgkmcnt(4)
	v_mfma_f32_16x16x32_bf16 v[82:85], v[2:5], v[86:89], v[66:69]
	v_mfma_f32_16x16x32_bf16 v[138:141], v[6:9], v[86:89], v[26:29]
	ds_read_b64_tr_b16 v[26:27], v222 offset:0x4400
	ds_read_b64_tr_b16 v[28:29], v250 offset:0x4400
	s_waitcnt lgkmcnt(4)
	v_mfma_f32_16x16x32_bf16 v[86:89], v[2:5], v[18:21], v[70:73]
	v_mfma_f32_16x16x32_bf16 v[142:145], v[6:9], v[18:21], v[58:61]
	ds_read_b64_tr_b16 v[18:19], v220 offset:0x4600
	ds_read_b64_tr_b16 v[20:21], v221 offset:0x4600
	s_waitcnt lgkmcnt(4)
	v_mfma_f32_16x16x32_bf16 v[90:93], v[2:5], v[22:25], v[178:181]
	v_mfma_f32_16x16x32_bf16 v[146:149], v[6:9], v[22:25], v[150:153]
	ds_read_b64_tr_b16 v[22:23], v222 offset:0x4600
	ds_read_b64_tr_b16 v[24:25], v250 offset:0x4600
	s_waitcnt lgkmcnt(4)
	v_mfma_f32_16x16x32_bf16 v[94:97], v[2:5], v[26:29], v[166:169]
	v_mfma_f32_16x16x32_bf16 v[150:153], v[6:9], v[26:29], v[162:165]
	ds_read_b64_tr_b16 v[26:27], v220 offset:0x6000
	ds_read_b64_tr_b16 v[28:29], v221 offset:0x6000
	s_waitcnt lgkmcnt(4)
	v_mfma_f32_16x16x32_bf16 v[98:101], v[2:5], v[18:21], v[192:195]
	v_mfma_f32_16x16x32_bf16 v[154:157], v[6:9], v[18:21], v[154:157]
	ds_read_b64_tr_b16 v[18:19], v222 offset:0x6000
	ds_read_b64_tr_b16 v[20:21], v250 offset:0x6000
	s_waitcnt lgkmcnt(4)
	v_mfma_f32_16x16x32_bf16 v[102:105], v[2:5], v[22:25], v[196:199]
	v_mfma_f32_16x16x32_bf16 v[158:161], v[6:9], v[22:25], v[200:203]
	ds_read_b64_tr_b16 v[22:23], v220 offset:0x6200
	ds_read_b64_tr_b16 v[24:25], v221 offset:0x6200
	s_waitcnt lgkmcnt(4)
	v_mfma_f32_16x16x32_bf16 v[106:109], v[2:5], v[26:29], v[110:113]
	v_mfma_f32_16x16x32_bf16 v[162:165], v[6:9], v[26:29], v[126:129]
	ds_read_b64_tr_b16 v[26:27], v222 offset:0x6200
	ds_read_b64_tr_b16 v[28:29], v250 offset:0x6200
	s_waitcnt lgkmcnt(4)
	v_mfma_f32_16x16x32_bf16 v[110:113], v[2:5], v[18:21], v[122:125]
	v_mfma_f32_16x16x32_bf16 v[166:169], v[6:9], v[18:21], v[118:121]
	ds_read_b64_tr_b16 v[18:19], v220 offset:0x6400
	ds_read_b64_tr_b16 v[20:21], v221 offset:0x6400
	s_waitcnt lgkmcnt(4)
	v_mfma_f32_16x16x32_bf16 v[114:117], v[2:5], v[22:25], v[204:207]
	v_mfma_f32_16x16x32_bf16 v[170:173], v[6:9], v[22:25], v[208:211]
	ds_read_b64_tr_b16 v[22:23], v222 offset:0x6400
	ds_read_b64_tr_b16 v[24:25], v250 offset:0x6400
	s_waitcnt lgkmcnt(4)
	v_mfma_f32_16x16x32_bf16 v[118:121], v[2:5], v[26:29], v[212:215]
	v_mfma_f32_16x16x32_bf16 v[174:177], v[6:9], v[26:29], v[216:219]
	ds_read_b64_tr_b16 v[26:27], v220 offset:0x6600
	ds_read_b64_tr_b16 v[28:29], v221 offset:0x6600
	s_waitcnt lgkmcnt(4)
	v_mfma_f32_16x16x32_bf16 v[122:125], v[2:5], v[18:21], v[226:229]
	v_mfma_f32_16x16x32_bf16 v[178:181], v[6:9], v[18:21], v[230:233]
	ds_read_b64_tr_b16 v[18:19], v222 offset:0x6600
	ds_read_b64_tr_b16 v[20:21], v250 offset:0x6600
	s_waitcnt lgkmcnt(4)
	v_mfma_f32_16x16x32_bf16 v[126:129], v[2:5], v[22:25], v[234:237]
	v_mfma_f32_16x16x32_bf16 v[182:185], v[6:9], v[22:25], v[238:241]
	s_waitcnt lgkmcnt(2)
	v_mfma_f32_16x16x32_bf16 v[66:69], v[2:5], v[26:29], v[242:245]
	v_mfma_f32_16x16x32_bf16 v[70:73], v[6:9], v[26:29], v[246:249]
	s_waitcnt lgkmcnt(0)
	v_mfma_f32_16x16x32_bf16 v[58:61], v[2:5], v[18:21], v[10:13]
	v_mfma_f32_16x16x32_bf16 v[62:65], v[6:9], v[18:21], v[14:17]
	s_cmp_ge_u32 s89, s80
	s_cbranch_scc1 .Ls1w_full
	s_waitcnt vmcnt(4)
	s_branch .Ls1w_done

.Ls1w_done:
	s_barrier
	s_setprio 3
	s_cselect_b64 s[34:35], -1, 0
	s_and_b64 vcc, exec, s[34:35]
	v_mbcnt_lo_u32_b32 v192, -1, 0
	v_mbcnt_hi_u32_b32 v192, -1, v192
	s_cbranch_vccnz .LBB0_194
	s_cmp_lt_u32 s19, 4
	s_cbranch_scc0 .Ls1b1_lag
	s_add_u32 s98, s8, s30
	s_addc_u32 s99, s9, s31
	s_mov_b32 m0, s62
	s_nop 0
	global_load_lds_dwordx4 v251, s[98:99]
	s_mov_b32 m0, s63
	s_nop 0
	global_load_lds_dwordx4 v251, s[8:9]
	s_mov_b32 m0, s66
	s_nop 0
	global_load_lds_dwordx4 v252, s[98:99]
	s_mov_b32 m0, s67
	s_nop 0
	global_load_lds_dwordx4 v252, s[8:9]
	s_branch .LBB0_194
.Ls1b1_lag:
	s_add_i32 s36, s68, s79
	s_addk_i32 s36, 0x80
	s_mul_hi_i32 s37, s36, 0xa000
	s_mul_i32 s36, s36, 0xa000
	s_add_u32 s36, s82, s36
	s_addc_u32 s37, s83, s37
	s_add_u32 s98, s36, 0x80
	s_addc_u32 s99, s37, 0
	s_mov_b32 m0, s71
	s_nop 0
	global_load_lds_dwordx4 v253, s[36:37]
	s_mov_b32 m0, s72
	s_nop 0
	global_load_lds_dwordx4 v253, s[98:99]
	s_mov_b32 m0, s75
	s_nop 0
	global_load_lds_dwordx4 v254, s[36:37]
	s_mov_b32 m0, s78
	s_nop 0
	global_load_lds_dwordx4 v254, s[98:99]

.LBB0_202:
	s_cmp_ge_u32 s19, 4
	s_cbranch_scc1 .Lstag_post_skip
	s_barrier
